# EpiPart f32 partial stores as 8x128B full lines (DPP lane-pair exchange) on top of previous
# baseline (speedup 1.0000x reference)
;     __device__ __forceinline__ void operator()(const f32x4 (&acc)[2][2][4][2], const Unit& u, int wr, int wc, int fr, int fq) const {
;         const int rowb = u.pm * BM - row0 + wr * 64 + fr, col0 = u.pn * BM + wc * 32 + 4 * fq; float* Ob = O + (size_t)u.pk * pstride;
; #pragma unroll
;         for (int ai = 0; ai < 2; ++ai)
; #pragma unroll
;             for (int m = 0; m < 4; ++m) {
;                 const size_t off = (size_t)(rowb + ai * HALF + m * 16) * ldc + col0;
; #pragma unroll
;                 for (int bj = 0; bj < 2; ++bj)
; #pragma unroll
;                     for (int n = 0; n < 2; ++n) *(f32x4*)(Ob + off + bj * HALF + n * 16) = acc[ai][bj][m][n];
;             }
.LBB0_210:
	v_lshl_or_b32 v144, s25, 8, v139
	s_ashr_i32 s25, s24, 31
	s_lshl_b64 s[24:25], s[24:25], 22
	s_add_u32 s24, s10, s24
	v_lshl_add_u32 v146, s65, 8, v138
	s_addc_u32 s25, s11, s25
	v_ashrrev_i32_e32 v145, 31, v144
	v_ashrrev_i32_e32 v147, 31, v146
	v_lshl_add_u64 v[144:145], v[144:145], 2, s[24:25]
	v_lshlrev_b64 v[148:149], 12, v[146:147]
	v_lshl_add_u64 v[148:149], v[144:145], 0, v[148:149]
	v_and_b32_e32 v160, 1, v186
	v_cmp_eq_u32_e32 vcc, 0, v160
	v_xor_b32_e32 v160, 1, v160
	s_movk_i32 s98, 0xfc0
	v_mov_b32_e32 v159, 0
	v_mad_u32_u24 v158, v160, s98, 64
	s_mov_b32 s98, 0x10000
	s_mov_b32 s99, 0
	v_lshl_add_u64 v[148:149], v[148:149], 0, v[158:159]
	v_cndmask_b32_dpp v150, v122, v126, vcc quad_perm:[1,0,3,2] row_mask:0xf bank_mask:0xf
	v_cndmask_b32_dpp v151, v123, v127, vcc quad_perm:[1,0,3,2] row_mask:0xf bank_mask:0xf
	v_cndmask_b32_dpp v152, v124, v128, vcc quad_perm:[1,0,3,2] row_mask:0xf bank_mask:0xf
	v_cndmask_b32_dpp v153, v125, v129, vcc quad_perm:[1,0,3,2] row_mask:0xf bank_mask:0xf
	v_cndmask_b32_dpp v154, v114, v118, vcc quad_perm:[1,0,3,2] row_mask:0xf bank_mask:0xf
	v_cndmask_b32_dpp v155, v115, v119, vcc quad_perm:[1,0,3,2] row_mask:0xf bank_mask:0xf
	v_cndmask_b32_dpp v156, v116, v120, vcc quad_perm:[1,0,3,2] row_mask:0xf bank_mask:0xf
	v_cndmask_b32_dpp v157, v117, v121, vcc quad_perm:[1,0,3,2] row_mask:0xf bank_mask:0xf
	s_not_b64 vcc, vcc
	v_cndmask_b32_dpp v122, v126, v122, vcc quad_perm:[1,0,3,2] row_mask:0xf bank_mask:0xf
	v_cndmask_b32_dpp v123, v127, v123, vcc quad_perm:[1,0,3,2] row_mask:0xf bank_mask:0xf
	v_cndmask_b32_dpp v124, v128, v124, vcc quad_perm:[1,0,3,2] row_mask:0xf bank_mask:0xf
	v_cndmask_b32_dpp v125, v129, v125, vcc quad_perm:[1,0,3,2] row_mask:0xf bank_mask:0xf
	v_cndmask_b32_dpp v114, v118, v114, vcc quad_perm:[1,0,3,2] row_mask:0xf bank_mask:0xf
	v_cndmask_b32_dpp v115, v119, v115, vcc quad_perm:[1,0,3,2] row_mask:0xf bank_mask:0xf
	v_cndmask_b32_dpp v116, v120, v116, vcc quad_perm:[1,0,3,2] row_mask:0xf bank_mask:0xf
	v_cndmask_b32_dpp v117, v121, v117, vcc quad_perm:[1,0,3,2] row_mask:0xf bank_mask:0xf
	s_not_b64 vcc, vcc
	global_store_dwordx4 v[148:149], v[150:153], off offset:-4096
	global_store_dwordx4 v[148:149], v[154:157], off offset:-3584
	global_store_dwordx4 v[148:149], v[122:125], off
	global_store_dwordx4 v[148:149], v[114:117], off offset:512
	s_nop 1
	v_lshl_add_u64 v[148:149], v[148:149], 0, s[98:99]
	v_cndmask_b32_dpp v162, v106, v110, vcc quad_perm:[1,0,3,2] row_mask:0xf bank_mask:0xf
	v_cndmask_b32_dpp v163, v107, v111, vcc quad_perm:[1,0,3,2] row_mask:0xf bank_mask:0xf
	v_cndmask_b32_dpp v164, v108, v112, vcc quad_perm:[1,0,3,2] row_mask:0xf bank_mask:0xf
	v_cndmask_b32_dpp v165, v109, v113, vcc quad_perm:[1,0,3,2] row_mask:0xf bank_mask:0xf
	v_cndmask_b32_dpp v166, v98, v102, vcc quad_perm:[1,0,3,2] row_mask:0xf bank_mask:0xf
	v_cndmask_b32_dpp v167, v99, v103, vcc quad_perm:[1,0,3,2] row_mask:0xf bank_mask:0xf
	v_cndmask_b32_dpp v168, v100, v104, vcc quad_perm:[1,0,3,2] row_mask:0xf bank_mask:0xf
	v_cndmask_b32_dpp v169, v101, v105, vcc quad_perm:[1,0,3,2] row_mask:0xf bank_mask:0xf
	s_not_b64 vcc, vcc
	v_cndmask_b32_dpp v106, v110, v106, vcc quad_perm:[1,0,3,2] row_mask:0xf bank_mask:0xf
	v_cndmask_b32_dpp v107, v111, v107, vcc quad_perm:[1,0,3,2] row_mask:0xf bank_mask:0xf
	v_cndmask_b32_dpp v108, v112, v108, vcc quad_perm:[1,0,3,2] row_mask:0xf bank_mask:0xf
	v_cndmask_b32_dpp v109, v113, v109, vcc quad_perm:[1,0,3,2] row_mask:0xf bank_mask:0xf
	v_cndmask_b32_dpp v98, v102, v98, vcc quad_perm:[1,0,3,2] row_mask:0xf bank_mask:0xf
	v_cndmask_b32_dpp v99, v103, v99, vcc quad_perm:[1,0,3,2] row_mask:0xf bank_mask:0xf
	v_cndmask_b32_dpp v100, v104, v100, vcc quad_perm:[1,0,3,2] row_mask:0xf bank_mask:0xf
	v_cndmask_b32_dpp v101, v105, v101, vcc quad_perm:[1,0,3,2] row_mask:0xf bank_mask:0xf
	s_not_b64 vcc, vcc
	global_store_dwordx4 v[148:149], v[162:165], off offset:-4096
	global_store_dwordx4 v[148:149], v[166:169], off offset:-3584
	global_store_dwordx4 v[148:149], v[106:109], off
	global_store_dwordx4 v[148:149], v[98:101], off offset:512
	s_nop 1
	v_lshl_add_u64 v[148:149], v[148:149], 0, s[98:99]
	v_cndmask_b32_dpp v150, v90, v94, vcc quad_perm:[1,0,3,2] row_mask:0xf bank_mask:0xf
	v_cndmask_b32_dpp v151, v91, v95, vcc quad_perm:[1,0,3,2] row_mask:0xf bank_mask:0xf
	v_cndmask_b32_dpp v152, v92, v96, vcc quad_perm:[1,0,3,2] row_mask:0xf bank_mask:0xf
	v_cndmask_b32_dpp v153, v93, v97, vcc quad_perm:[1,0,3,2] row_mask:0xf bank_mask:0xf
	v_cndmask_b32_dpp v154, v82, v86, vcc quad_perm:[1,0,3,2] row_mask:0xf bank_mask:0xf
	v_cndmask_b32_dpp v155, v83, v87, vcc quad_perm:[1,0,3,2] row_mask:0xf bank_mask:0xf
	v_cndmask_b32_dpp v156, v84, v88, vcc quad_perm:[1,0,3,2] row_mask:0xf bank_mask:0xf
	v_cndmask_b32_dpp v157, v85, v89, vcc quad_perm:[1,0,3,2] row_mask:0xf bank_mask:0xf
	s_not_b64 vcc, vcc
	v_cndmask_b32_dpp v90, v94, v90, vcc quad_perm:[1,0,3,2] row_mask:0xf bank_mask:0xf
	v_cndmask_b32_dpp v91, v95, v91, vcc quad_perm:[1,0,3,2] row_mask:0xf bank_mask:0xf
	v_cndmask_b32_dpp v92, v96, v92, vcc quad_perm:[1,0,3,2] row_mask:0xf bank_mask:0xf
	v_cndmask_b32_dpp v93, v97, v93, vcc quad_perm:[1,0,3,2] row_mask:0xf bank_mask:0xf
	v_cndmask_b32_dpp v82, v86, v82, vcc quad_perm:[1,0,3,2] row_mask:0xf bank_mask:0xf
	v_cndmask_b32_dpp v83, v87, v83, vcc quad_perm:[1,0,3,2] row_mask:0xf bank_mask:0xf
	v_cndmask_b32_dpp v84, v88, v84, vcc quad_perm:[1,0,3,2] row_mask:0xf bank_mask:0xf
	v_cndmask_b32_dpp v85, v89, v85, vcc quad_perm:[1,0,3,2] row_mask:0xf bank_mask:0xf
	s_not_b64 vcc, vcc
	global_store_dwordx4 v[148:149], v[150:153], off offset:-4096
;     __device__ __forceinline__ void operator()(const f32x4 (&acc)[2][2][4][2], const Unit& u, int wr, int wc, int fr, int fq) const {
;         const int rowb = u.pm * BM - row0 + wr * 64 + fr, col0 = u.pn * BM + wc * 32 + 4 * fq; float* Ob = O + (size_t)u.pk * pstride;
; #pragma unroll
;         for (int ai = 0; ai < 2; ++ai)
; #pragma unroll
;             for (int m = 0; m < 4; ++m) {
;                 const size_t off = (size_t)(rowb + ai * HALF + m * 16) * ldc + col0;
; #pragma unroll
;                 for (int bj = 0; bj < 2; ++bj)
; #pragma unroll
;                     for (int n = 0; n < 2; ++n) *(f32x4*)(Ob + off + bj * HALF + n * 16) = acc[ai][bj][m][n];
;             }
	global_store_dwordx4 v[148:149], v[154:157], off offset:-3584
	global_store_dwordx4 v[148:149], v[90:93], off
	global_store_dwordx4 v[148:149], v[82:85], off offset:512
	s_nop 1
	v_lshl_add_u64 v[148:149], v[148:149], 0, s[98:99]
	v_cndmask_b32_dpp v162, v74, v78, vcc quad_perm:[1,0,3,2] row_mask:0xf bank_mask:0xf
	v_cndmask_b32_dpp v163, v75, v79, vcc quad_perm:[1,0,3,2] row_mask:0xf bank_mask:0xf
	v_cndmask_b32_dpp v164, v76, v80, vcc quad_perm:[1,0,3,2] row_mask:0xf bank_mask:0xf
	v_cndmask_b32_dpp v165, v77, v81, vcc quad_perm:[1,0,3,2] row_mask:0xf bank_mask:0xf
	v_cndmask_b32_dpp v166, v66, v70, vcc quad_perm:[1,0,3,2] row_mask:0xf bank_mask:0xf
	v_cndmask_b32_dpp v167, v67, v71, vcc quad_perm:[1,0,3,2] row_mask:0xf bank_mask:0xf
	v_cndmask_b32_dpp v168, v68, v72, vcc quad_perm:[1,0,3,2] row_mask:0xf bank_mask:0xf
	v_cndmask_b32_dpp v169, v69, v73, vcc quad_perm:[1,0,3,2] row_mask:0xf bank_mask:0xf
	s_not_b64 vcc, vcc
	v_cndmask_b32_dpp v74, v78, v74, vcc quad_perm:[1,0,3,2] row_mask:0xf bank_mask:0xf
	v_cndmask_b32_dpp v75, v79, v75, vcc quad_perm:[1,0,3,2] row_mask:0xf bank_mask:0xf
	v_cndmask_b32_dpp v76, v80, v76, vcc quad_perm:[1,0,3,2] row_mask:0xf bank_mask:0xf
	v_cndmask_b32_dpp v77, v81, v77, vcc quad_perm:[1,0,3,2] row_mask:0xf bank_mask:0xf
	v_cndmask_b32_dpp v66, v70, v66, vcc quad_perm:[1,0,3,2] row_mask:0xf bank_mask:0xf
	v_cndmask_b32_dpp v67, v71, v67, vcc quad_perm:[1,0,3,2] row_mask:0xf bank_mask:0xf
	v_cndmask_b32_dpp v68, v72, v68, vcc quad_perm:[1,0,3,2] row_mask:0xf bank_mask:0xf
	v_cndmask_b32_dpp v69, v73, v69, vcc quad_perm:[1,0,3,2] row_mask:0xf bank_mask:0xf
	s_not_b64 vcc, vcc
	global_store_dwordx4 v[148:149], v[162:165], off offset:-4096
	global_store_dwordx4 v[148:149], v[166:169], off offset:-3584
	global_store_dwordx4 v[148:149], v[74:77], off
	global_store_dwordx4 v[148:149], v[66:69], off offset:512
	s_mov_b32 s98, 0x50000
	s_nop 0
	v_lshl_add_u64 v[148:149], v[148:149], 0, s[98:99]
	s_mov_b32 s98, 0x10000
	v_cndmask_b32_dpp v150, v58, v62, vcc quad_perm:[1,0,3,2] row_mask:0xf bank_mask:0xf
	v_cndmask_b32_dpp v151, v59, v63, vcc quad_perm:[1,0,3,2] row_mask:0xf bank_mask:0xf
	v_cndmask_b32_dpp v152, v60, v64, vcc quad_perm:[1,0,3,2] row_mask:0xf bank_mask:0xf
	v_cndmask_b32_dpp v153, v61, v65, vcc quad_perm:[1,0,3,2] row_mask:0xf bank_mask:0xf
	v_cndmask_b32_dpp v154, v50, v54, vcc quad_perm:[1,0,3,2] row_mask:0xf bank_mask:0xf
	v_cndmask_b32_dpp v155, v51, v55, vcc quad_perm:[1,0,3,2] row_mask:0xf bank_mask:0xf
	v_cndmask_b32_dpp v156, v52, v56, vcc quad_perm:[1,0,3,2] row_mask:0xf bank_mask:0xf
	v_cndmask_b32_dpp v157, v53, v57, vcc quad_perm:[1,0,3,2] row_mask:0xf bank_mask:0xf
	s_not_b64 vcc, vcc
	v_cndmask_b32_dpp v58, v62, v58, vcc quad_perm:[1,0,3,2] row_mask:0xf bank_mask:0xf
	v_cndmask_b32_dpp v59, v63, v59, vcc quad_perm:[1,0,3,2] row_mask:0xf bank_mask:0xf
	v_cndmask_b32_dpp v60, v64, v60, vcc quad_perm:[1,0,3,2] row_mask:0xf bank_mask:0xf
	v_cndmask_b32_dpp v61, v65, v61, vcc quad_perm:[1,0,3,2] row_mask:0xf bank_mask:0xf
	v_cndmask_b32_dpp v50, v54, v50, vcc quad_perm:[1,0,3,2] row_mask:0xf bank_mask:0xf
	v_cndmask_b32_dpp v51, v55, v51, vcc quad_perm:[1,0,3,2] row_mask:0xf bank_mask:0xf
	v_cndmask_b32_dpp v52, v56, v52, vcc quad_perm:[1,0,3,2] row_mask:0xf bank_mask:0xf
	v_cndmask_b32_dpp v53, v57, v53, vcc quad_perm:[1,0,3,2] row_mask:0xf bank_mask:0xf
	s_not_b64 vcc, vcc
	global_store_dwordx4 v[148:149], v[150:153], off offset:-4096
	global_store_dwordx4 v[148:149], v[154:157], off offset:-3584
	global_store_dwordx4 v[148:149], v[58:61], off
	global_store_dwordx4 v[148:149], v[50:53], off offset:512
	s_nop 1
	v_lshl_add_u64 v[148:149], v[148:149], 0, s[98:99]
	v_cndmask_b32_dpp v162, v42, v46, vcc quad_perm:[1,0,3,2] row_mask:0xf bank_mask:0xf
	v_cndmask_b32_dpp v163, v43, v47, vcc quad_perm:[1,0,3,2] row_mask:0xf bank_mask:0xf
	v_cndmask_b32_dpp v164, v44, v48, vcc quad_perm:[1,0,3,2] row_mask:0xf bank_mask:0xf
	v_cndmask_b32_dpp v165, v45, v49, vcc quad_perm:[1,0,3,2] row_mask:0xf bank_mask:0xf
	v_cndmask_b32_dpp v166, v34, v38, vcc quad_perm:[1,0,3,2] row_mask:0xf bank_mask:0xf
	v_cndmask_b32_dpp v167, v35, v39, vcc quad_perm:[1,0,3,2] row_mask:0xf bank_mask:0xf
	v_cndmask_b32_dpp v168, v36, v40, vcc quad_perm:[1,0,3,2] row_mask:0xf bank_mask:0xf
	v_cndmask_b32_dpp v169, v37, v41, vcc quad_perm:[1,0,3,2] row_mask:0xf bank_mask:0xf
	s_not_b64 vcc, vcc
	v_cndmask_b32_dpp v42, v46, v42, vcc quad_perm:[1,0,3,2] row_mask:0xf bank_mask:0xf
;     __device__ __forceinline__ void operator()(const f32x4 (&acc)[2][2][4][2], const Unit& u, int wr, int wc, int fr, int fq) const {
;         const int rowb = u.pm * BM - row0 + wr * 64 + fr, col0 = u.pn * BM + wc * 32 + 4 * fq; float* Ob = O + (size_t)u.pk * pstride;
; #pragma unroll
;         for (int ai = 0; ai < 2; ++ai)
; #pragma unroll
;             for (int m = 0; m < 4; ++m) {
;                 const size_t off = (size_t)(rowb + ai * HALF + m * 16) * ldc + col0;
; #pragma unroll
;                 for (int bj = 0; bj < 2; ++bj)
; #pragma unroll
;                     for (int n = 0; n < 2; ++n) *(f32x4*)(Ob + off + bj * HALF + n * 16) = acc[ai][bj][m][n];
;             }
	v_cndmask_b32_dpp v43, v47, v43, vcc quad_perm:[1,0,3,2] row_mask:0xf bank_mask:0xf
	v_cndmask_b32_dpp v44, v48, v44, vcc quad_perm:[1,0,3,2] row_mask:0xf bank_mask:0xf
	v_cndmask_b32_dpp v45, v49, v45, vcc quad_perm:[1,0,3,2] row_mask:0xf bank_mask:0xf
	v_cndmask_b32_dpp v34, v38, v34, vcc quad_perm:[1,0,3,2] row_mask:0xf bank_mask:0xf
	v_cndmask_b32_dpp v35, v39, v35, vcc quad_perm:[1,0,3,2] row_mask:0xf bank_mask:0xf
	v_cndmask_b32_dpp v36, v40, v36, vcc quad_perm:[1,0,3,2] row_mask:0xf bank_mask:0xf
	v_cndmask_b32_dpp v37, v41, v37, vcc quad_perm:[1,0,3,2] row_mask:0xf bank_mask:0xf
	s_not_b64 vcc, vcc
	global_store_dwordx4 v[148:149], v[162:165], off offset:-4096
	global_store_dwordx4 v[148:149], v[166:169], off offset:-3584
	global_store_dwordx4 v[148:149], v[42:45], off
	global_store_dwordx4 v[148:149], v[34:37], off offset:512
	s_nop 1
	v_lshl_add_u64 v[148:149], v[148:149], 0, s[98:99]
	v_cndmask_b32_dpp v150, v26, v30, vcc quad_perm:[1,0,3,2] row_mask:0xf bank_mask:0xf
	v_cndmask_b32_dpp v151, v27, v31, vcc quad_perm:[1,0,3,2] row_mask:0xf bank_mask:0xf
	v_cndmask_b32_dpp v152, v28, v32, vcc quad_perm:[1,0,3,2] row_mask:0xf bank_mask:0xf
	v_cndmask_b32_dpp v153, v29, v33, vcc quad_perm:[1,0,3,2] row_mask:0xf bank_mask:0xf
	v_cndmask_b32_dpp v154, v18, v22, vcc quad_perm:[1,0,3,2] row_mask:0xf bank_mask:0xf
	v_cndmask_b32_dpp v155, v19, v23, vcc quad_perm:[1,0,3,2] row_mask:0xf bank_mask:0xf
	v_cndmask_b32_dpp v156, v20, v24, vcc quad_perm:[1,0,3,2] row_mask:0xf bank_mask:0xf
	v_cndmask_b32_dpp v157, v21, v25, vcc quad_perm:[1,0,3,2] row_mask:0xf bank_mask:0xf
	s_not_b64 vcc, vcc
	v_cndmask_b32_dpp v26, v30, v26, vcc quad_perm:[1,0,3,2] row_mask:0xf bank_mask:0xf
	v_cndmask_b32_dpp v27, v31, v27, vcc quad_perm:[1,0,3,2] row_mask:0xf bank_mask:0xf
	v_cndmask_b32_dpp v28, v32, v28, vcc quad_perm:[1,0,3,2] row_mask:0xf bank_mask:0xf
	v_cndmask_b32_dpp v29, v33, v29, vcc quad_perm:[1,0,3,2] row_mask:0xf bank_mask:0xf
	v_cndmask_b32_dpp v18, v22, v18, vcc quad_perm:[1,0,3,2] row_mask:0xf bank_mask:0xf
	v_cndmask_b32_dpp v19, v23, v19, vcc quad_perm:[1,0,3,2] row_mask:0xf bank_mask:0xf
	v_cndmask_b32_dpp v20, v24, v20, vcc quad_perm:[1,0,3,2] row_mask:0xf bank_mask:0xf
	v_cndmask_b32_dpp v21, v25, v21, vcc quad_perm:[1,0,3,2] row_mask:0xf bank_mask:0xf
	s_not_b64 vcc, vcc
	global_store_dwordx4 v[148:149], v[150:153], off offset:-4096
	global_store_dwordx4 v[148:149], v[154:157], off offset:-3584
	global_store_dwordx4 v[148:149], v[26:29], off
	global_store_dwordx4 v[148:149], v[18:21], off offset:512
	s_nop 1
	v_lshl_add_u64 v[148:149], v[148:149], 0, s[98:99]
	v_cndmask_b32_dpp v162, v10, v14, vcc quad_perm:[1,0,3,2] row_mask:0xf bank_mask:0xf
	v_cndmask_b32_dpp v163, v11, v15, vcc quad_perm:[1,0,3,2] row_mask:0xf bank_mask:0xf
	v_cndmask_b32_dpp v164, v12, v16, vcc quad_perm:[1,0,3,2] row_mask:0xf bank_mask:0xf
	v_cndmask_b32_dpp v165, v13, v17, vcc quad_perm:[1,0,3,2] row_mask:0xf bank_mask:0xf
	v_cndmask_b32_dpp v166, v2, v6, vcc quad_perm:[1,0,3,2] row_mask:0xf bank_mask:0xf
	v_cndmask_b32_dpp v167, v3, v7, vcc quad_perm:[1,0,3,2] row_mask:0xf bank_mask:0xf
	v_cndmask_b32_dpp v168, v4, v8, vcc quad_perm:[1,0,3,2] row_mask:0xf bank_mask:0xf
	v_cndmask_b32_dpp v169, v5, v9, vcc quad_perm:[1,0,3,2] row_mask:0xf bank_mask:0xf
	s_not_b64 vcc, vcc
	v_cndmask_b32_dpp v10, v14, v10, vcc quad_perm:[1,0,3,2] row_mask:0xf bank_mask:0xf
	v_cndmask_b32_dpp v11, v15, v11, vcc quad_perm:[1,0,3,2] row_mask:0xf bank_mask:0xf
	v_cndmask_b32_dpp v12, v16, v12, vcc quad_perm:[1,0,3,2] row_mask:0xf bank_mask:0xf
	v_cndmask_b32_dpp v13, v17, v13, vcc quad_perm:[1,0,3,2] row_mask:0xf bank_mask:0xf
	v_cndmask_b32_dpp v2, v6, v2, vcc quad_perm:[1,0,3,2] row_mask:0xf bank_mask:0xf
	v_cndmask_b32_dpp v3, v7, v3, vcc quad_perm:[1,0,3,2] row_mask:0xf bank_mask:0xf
	v_cndmask_b32_dpp v4, v8, v4, vcc quad_perm:[1,0,3,2] row_mask:0xf bank_mask:0xf
	v_cndmask_b32_dpp v5, v9, v5, vcc quad_perm:[1,0,3,2] row_mask:0xf bank_mask:0xf
	s_not_b64 vcc, vcc
	global_store_dwordx4 v[148:149], v[162:165], off offset:-4096
	global_store_dwordx4 v[148:149], v[166:169], off offset:-3584
	global_store_dwordx4 v[148:149], v[10:13], off
	global_store_dwordx4 v[148:149], v[2:5], off offset:512
	s_and_b64 vcc, exec, s[4:5]
	s_mov_b64 s[4:5], -1
	s_cbranch_vccnz .LBB0_198
	s_andn2_b64 vcc, exec, s[12:13]
	s_cbranch_vccnz .LBB0_197
	s_barrier
	s_branch .LBB0_197

;     __device__ __forceinline__ void operator()(const f32x4 (&acc)[2][2][4][2], const Unit& u, int wr, int wc, int fr, int fq) const {
;         const int rowb = u.pm * BM - row0 + wr * 64 + fr, col0 = u.pn * BM + wc * 32 + 4 * fq; float* Ob = O + (size_t)u.pk * pstride;
; #pragma unroll
;         for (int ai = 0; ai < 2; ++ai)
; #pragma unroll
;             for (int m = 0; m < 4; ++m) {
;                 const size_t off = (size_t)(rowb + ai * HALF + m * 16) * ldc + col0;
; #pragma unroll
;                 for (int bj = 0; bj < 2; ++bj)
; #pragma unroll
;                     for (int n = 0; n < 2; ++n) *(f32x4*)(Ob + off + bj * HALF + n * 16) = acc[ai][bj][m][n];
;             }
.LBB0_1485:
	v_lshl_or_b32 v144, s29, 8, v139
	s_ashr_i32 s29, s28, 31
	s_lshl_b64 s[28:29], s[28:29], 22
	s_add_u32 s28, s10, s28
	v_lshl_add_u32 v146, s72, 8, v138
	s_addc_u32 s29, s11, s29
	v_ashrrev_i32_e32 v145, 31, v144
	v_ashrrev_i32_e32 v147, 31, v146
	v_lshl_add_u64 v[144:145], v[144:145], 2, s[28:29]
	v_lshlrev_b64 v[148:149], 12, v[146:147]
	v_lshl_add_u64 v[148:149], v[144:145], 0, v[148:149]
	v_and_b32_e32 v160, 1, v186
	v_cmp_eq_u32_e32 vcc, 0, v160
	v_xor_b32_e32 v160, 1, v160
	s_movk_i32 s98, 0xfc0
	v_mov_b32_e32 v159, 0
	v_mad_u32_u24 v158, v160, s98, 64
	s_mov_b32 s98, 0x10000
	s_mov_b32 s99, 0
	v_lshl_add_u64 v[148:149], v[148:149], 0, v[158:159]
	v_cndmask_b32_dpp v150, v122, v126, vcc quad_perm:[1,0,3,2] row_mask:0xf bank_mask:0xf
	v_cndmask_b32_dpp v151, v123, v127, vcc quad_perm:[1,0,3,2] row_mask:0xf bank_mask:0xf
	v_cndmask_b32_dpp v152, v124, v128, vcc quad_perm:[1,0,3,2] row_mask:0xf bank_mask:0xf
	v_cndmask_b32_dpp v153, v125, v129, vcc quad_perm:[1,0,3,2] row_mask:0xf bank_mask:0xf
	v_cndmask_b32_dpp v154, v114, v118, vcc quad_perm:[1,0,3,2] row_mask:0xf bank_mask:0xf
	v_cndmask_b32_dpp v155, v115, v119, vcc quad_perm:[1,0,3,2] row_mask:0xf bank_mask:0xf
	v_cndmask_b32_dpp v156, v116, v120, vcc quad_perm:[1,0,3,2] row_mask:0xf bank_mask:0xf
	v_cndmask_b32_dpp v157, v117, v121, vcc quad_perm:[1,0,3,2] row_mask:0xf bank_mask:0xf
	s_not_b64 vcc, vcc
	v_cndmask_b32_dpp v122, v126, v122, vcc quad_perm:[1,0,3,2] row_mask:0xf bank_mask:0xf
	v_cndmask_b32_dpp v123, v127, v123, vcc quad_perm:[1,0,3,2] row_mask:0xf bank_mask:0xf
	v_cndmask_b32_dpp v124, v128, v124, vcc quad_perm:[1,0,3,2] row_mask:0xf bank_mask:0xf
	v_cndmask_b32_dpp v125, v129, v125, vcc quad_perm:[1,0,3,2] row_mask:0xf bank_mask:0xf
	v_cndmask_b32_dpp v114, v118, v114, vcc quad_perm:[1,0,3,2] row_mask:0xf bank_mask:0xf
	v_cndmask_b32_dpp v115, v119, v115, vcc quad_perm:[1,0,3,2] row_mask:0xf bank_mask:0xf
	v_cndmask_b32_dpp v116, v120, v116, vcc quad_perm:[1,0,3,2] row_mask:0xf bank_mask:0xf
	v_cndmask_b32_dpp v117, v121, v117, vcc quad_perm:[1,0,3,2] row_mask:0xf bank_mask:0xf
	s_not_b64 vcc, vcc
	global_store_dwordx4 v[148:149], v[150:153], off offset:-4096
	global_store_dwordx4 v[148:149], v[154:157], off offset:-3584
	global_store_dwordx4 v[148:149], v[122:125], off
	global_store_dwordx4 v[148:149], v[114:117], off offset:512
	s_nop 1
	v_lshl_add_u64 v[148:149], v[148:149], 0, s[98:99]
	v_cndmask_b32_dpp v162, v106, v110, vcc quad_perm:[1,0,3,2] row_mask:0xf bank_mask:0xf
	v_cndmask_b32_dpp v163, v107, v111, vcc quad_perm:[1,0,3,2] row_mask:0xf bank_mask:0xf
	v_cndmask_b32_dpp v164, v108, v112, vcc quad_perm:[1,0,3,2] row_mask:0xf bank_mask:0xf
	v_cndmask_b32_dpp v165, v109, v113, vcc quad_perm:[1,0,3,2] row_mask:0xf bank_mask:0xf
	v_cndmask_b32_dpp v166, v98, v102, vcc quad_perm:[1,0,3,2] row_mask:0xf bank_mask:0xf
	v_cndmask_b32_dpp v167, v99, v103, vcc quad_perm:[1,0,3,2] row_mask:0xf bank_mask:0xf
	v_cndmask_b32_dpp v168, v100, v104, vcc quad_perm:[1,0,3,2] row_mask:0xf bank_mask:0xf
	v_cndmask_b32_dpp v169, v101, v105, vcc quad_perm:[1,0,3,2] row_mask:0xf bank_mask:0xf
	s_not_b64 vcc, vcc
	v_cndmask_b32_dpp v106, v110, v106, vcc quad_perm:[1,0,3,2] row_mask:0xf bank_mask:0xf
	v_cndmask_b32_dpp v107, v111, v107, vcc quad_perm:[1,0,3,2] row_mask:0xf bank_mask:0xf
	v_cndmask_b32_dpp v108, v112, v108, vcc quad_perm:[1,0,3,2] row_mask:0xf bank_mask:0xf
	v_cndmask_b32_dpp v109, v113, v109, vcc quad_perm:[1,0,3,2] row_mask:0xf bank_mask:0xf
	v_cndmask_b32_dpp v98, v102, v98, vcc quad_perm:[1,0,3,2] row_mask:0xf bank_mask:0xf
	v_cndmask_b32_dpp v99, v103, v99, vcc quad_perm:[1,0,3,2] row_mask:0xf bank_mask:0xf
	v_cndmask_b32_dpp v100, v104, v100, vcc quad_perm:[1,0,3,2] row_mask:0xf bank_mask:0xf
	v_cndmask_b32_dpp v101, v105, v101, vcc quad_perm:[1,0,3,2] row_mask:0xf bank_mask:0xf
	s_not_b64 vcc, vcc
	global_store_dwordx4 v[148:149], v[162:165], off offset:-4096
	global_store_dwordx4 v[148:149], v[166:169], off offset:-3584
	global_store_dwordx4 v[148:149], v[106:109], off
	global_store_dwordx4 v[148:149], v[98:101], off offset:512
	s_nop 1
	v_lshl_add_u64 v[148:149], v[148:149], 0, s[98:99]
	v_cndmask_b32_dpp v150, v90, v94, vcc quad_perm:[1,0,3,2] row_mask:0xf bank_mask:0xf
	v_cndmask_b32_dpp v151, v91, v95, vcc quad_perm:[1,0,3,2] row_mask:0xf bank_mask:0xf
	v_cndmask_b32_dpp v152, v92, v96, vcc quad_perm:[1,0,3,2] row_mask:0xf bank_mask:0xf
	v_cndmask_b32_dpp v153, v93, v97, vcc quad_perm:[1,0,3,2] row_mask:0xf bank_mask:0xf
	v_cndmask_b32_dpp v154, v82, v86, vcc quad_perm:[1,0,3,2] row_mask:0xf bank_mask:0xf
	v_cndmask_b32_dpp v155, v83, v87, vcc quad_perm:[1,0,3,2] row_mask:0xf bank_mask:0xf
	v_cndmask_b32_dpp v156, v84, v88, vcc quad_perm:[1,0,3,2] row_mask:0xf bank_mask:0xf
	v_cndmask_b32_dpp v157, v85, v89, vcc quad_perm:[1,0,3,2] row_mask:0xf bank_mask:0xf
	s_not_b64 vcc, vcc
	v_cndmask_b32_dpp v90, v94, v90, vcc quad_perm:[1,0,3,2] row_mask:0xf bank_mask:0xf
	v_cndmask_b32_dpp v91, v95, v91, vcc quad_perm:[1,0,3,2] row_mask:0xf bank_mask:0xf
	v_cndmask_b32_dpp v92, v96, v92, vcc quad_perm:[1,0,3,2] row_mask:0xf bank_mask:0xf
	v_cndmask_b32_dpp v93, v97, v93, vcc quad_perm:[1,0,3,2] row_mask:0xf bank_mask:0xf
	v_cndmask_b32_dpp v82, v86, v82, vcc quad_perm:[1,0,3,2] row_mask:0xf bank_mask:0xf
	v_cndmask_b32_dpp v83, v87, v83, vcc quad_perm:[1,0,3,2] row_mask:0xf bank_mask:0xf
	v_cndmask_b32_dpp v84, v88, v84, vcc quad_perm:[1,0,3,2] row_mask:0xf bank_mask:0xf
	v_cndmask_b32_dpp v85, v89, v85, vcc quad_perm:[1,0,3,2] row_mask:0xf bank_mask:0xf
	s_not_b64 vcc, vcc
	global_store_dwordx4 v[148:149], v[150:153], off offset:-4096
;     __device__ __forceinline__ void operator()(const f32x4 (&acc)[2][2][4][2], const Unit& u, int wr, int wc, int fr, int fq) const {
;         const int rowb = u.pm * BM - row0 + wr * 64 + fr, col0 = u.pn * BM + wc * 32 + 4 * fq; float* Ob = O + (size_t)u.pk * pstride;
; #pragma unroll
;         for (int ai = 0; ai < 2; ++ai)
; #pragma unroll
;             for (int m = 0; m < 4; ++m) {
;                 const size_t off = (size_t)(rowb + ai * HALF + m * 16) * ldc + col0;
; #pragma unroll
;                 for (int bj = 0; bj < 2; ++bj)
; #pragma unroll
;                     for (int n = 0; n < 2; ++n) *(f32x4*)(Ob + off + bj * HALF + n * 16) = acc[ai][bj][m][n];
;             }
	global_store_dwordx4 v[148:149], v[154:157], off offset:-3584
	global_store_dwordx4 v[148:149], v[90:93], off
	global_store_dwordx4 v[148:149], v[82:85], off offset:512
	s_nop 1
	v_lshl_add_u64 v[148:149], v[148:149], 0, s[98:99]
	v_cndmask_b32_dpp v162, v74, v78, vcc quad_perm:[1,0,3,2] row_mask:0xf bank_mask:0xf
	v_cndmask_b32_dpp v163, v75, v79, vcc quad_perm:[1,0,3,2] row_mask:0xf bank_mask:0xf
	v_cndmask_b32_dpp v164, v76, v80, vcc quad_perm:[1,0,3,2] row_mask:0xf bank_mask:0xf
	v_cndmask_b32_dpp v165, v77, v81, vcc quad_perm:[1,0,3,2] row_mask:0xf bank_mask:0xf
	v_cndmask_b32_dpp v166, v66, v70, vcc quad_perm:[1,0,3,2] row_mask:0xf bank_mask:0xf
	v_cndmask_b32_dpp v167, v67, v71, vcc quad_perm:[1,0,3,2] row_mask:0xf bank_mask:0xf
	v_cndmask_b32_dpp v168, v68, v72, vcc quad_perm:[1,0,3,2] row_mask:0xf bank_mask:0xf
	v_cndmask_b32_dpp v169, v69, v73, vcc quad_perm:[1,0,3,2] row_mask:0xf bank_mask:0xf
	s_not_b64 vcc, vcc
	v_cndmask_b32_dpp v74, v78, v74, vcc quad_perm:[1,0,3,2] row_mask:0xf bank_mask:0xf
	v_cndmask_b32_dpp v75, v79, v75, vcc quad_perm:[1,0,3,2] row_mask:0xf bank_mask:0xf
	v_cndmask_b32_dpp v76, v80, v76, vcc quad_perm:[1,0,3,2] row_mask:0xf bank_mask:0xf
	v_cndmask_b32_dpp v77, v81, v77, vcc quad_perm:[1,0,3,2] row_mask:0xf bank_mask:0xf
	v_cndmask_b32_dpp v66, v70, v66, vcc quad_perm:[1,0,3,2] row_mask:0xf bank_mask:0xf
	v_cndmask_b32_dpp v67, v71, v67, vcc quad_perm:[1,0,3,2] row_mask:0xf bank_mask:0xf
	v_cndmask_b32_dpp v68, v72, v68, vcc quad_perm:[1,0,3,2] row_mask:0xf bank_mask:0xf
	v_cndmask_b32_dpp v69, v73, v69, vcc quad_perm:[1,0,3,2] row_mask:0xf bank_mask:0xf
	s_not_b64 vcc, vcc
	global_store_dwordx4 v[148:149], v[162:165], off offset:-4096
	global_store_dwordx4 v[148:149], v[166:169], off offset:-3584
	global_store_dwordx4 v[148:149], v[74:77], off
	global_store_dwordx4 v[148:149], v[66:69], off offset:512
	s_mov_b32 s98, 0x50000
	s_nop 0
	v_lshl_add_u64 v[148:149], v[148:149], 0, s[98:99]
	s_mov_b32 s98, 0x10000
	v_cndmask_b32_dpp v150, v58, v62, vcc quad_perm:[1,0,3,2] row_mask:0xf bank_mask:0xf
	v_cndmask_b32_dpp v151, v59, v63, vcc quad_perm:[1,0,3,2] row_mask:0xf bank_mask:0xf
	v_cndmask_b32_dpp v152, v60, v64, vcc quad_perm:[1,0,3,2] row_mask:0xf bank_mask:0xf
	v_cndmask_b32_dpp v153, v61, v65, vcc quad_perm:[1,0,3,2] row_mask:0xf bank_mask:0xf
	v_cndmask_b32_dpp v154, v50, v54, vcc quad_perm:[1,0,3,2] row_mask:0xf bank_mask:0xf
	v_cndmask_b32_dpp v155, v51, v55, vcc quad_perm:[1,0,3,2] row_mask:0xf bank_mask:0xf
	v_cndmask_b32_dpp v156, v52, v56, vcc quad_perm:[1,0,3,2] row_mask:0xf bank_mask:0xf
	v_cndmask_b32_dpp v157, v53, v57, vcc quad_perm:[1,0,3,2] row_mask:0xf bank_mask:0xf
	s_not_b64 vcc, vcc
	v_cndmask_b32_dpp v58, v62, v58, vcc quad_perm:[1,0,3,2] row_mask:0xf bank_mask:0xf
	v_cndmask_b32_dpp v59, v63, v59, vcc quad_perm:[1,0,3,2] row_mask:0xf bank_mask:0xf
	v_cndmask_b32_dpp v60, v64, v60, vcc quad_perm:[1,0,3,2] row_mask:0xf bank_mask:0xf
	v_cndmask_b32_dpp v61, v65, v61, vcc quad_perm:[1,0,3,2] row_mask:0xf bank_mask:0xf
	v_cndmask_b32_dpp v50, v54, v50, vcc quad_perm:[1,0,3,2] row_mask:0xf bank_mask:0xf
	v_cndmask_b32_dpp v51, v55, v51, vcc quad_perm:[1,0,3,2] row_mask:0xf bank_mask:0xf
	v_cndmask_b32_dpp v52, v56, v52, vcc quad_perm:[1,0,3,2] row_mask:0xf bank_mask:0xf
	v_cndmask_b32_dpp v53, v57, v53, vcc quad_perm:[1,0,3,2] row_mask:0xf bank_mask:0xf
	s_not_b64 vcc, vcc
	global_store_dwordx4 v[148:149], v[150:153], off offset:-4096
	global_store_dwordx4 v[148:149], v[154:157], off offset:-3584
	global_store_dwordx4 v[148:149], v[58:61], off
	global_store_dwordx4 v[148:149], v[50:53], off offset:512
	s_nop 1
	v_lshl_add_u64 v[148:149], v[148:149], 0, s[98:99]
	v_cndmask_b32_dpp v162, v42, v46, vcc quad_perm:[1,0,3,2] row_mask:0xf bank_mask:0xf
	v_cndmask_b32_dpp v163, v43, v47, vcc quad_perm:[1,0,3,2] row_mask:0xf bank_mask:0xf
	v_cndmask_b32_dpp v164, v44, v48, vcc quad_perm:[1,0,3,2] row_mask:0xf bank_mask:0xf
	v_cndmask_b32_dpp v165, v45, v49, vcc quad_perm:[1,0,3,2] row_mask:0xf bank_mask:0xf
	v_cndmask_b32_dpp v166, v34, v38, vcc quad_perm:[1,0,3,2] row_mask:0xf bank_mask:0xf
	v_cndmask_b32_dpp v167, v35, v39, vcc quad_perm:[1,0,3,2] row_mask:0xf bank_mask:0xf
	v_cndmask_b32_dpp v168, v36, v40, vcc quad_perm:[1,0,3,2] row_mask:0xf bank_mask:0xf
	v_cndmask_b32_dpp v169, v37, v41, vcc quad_perm:[1,0,3,2] row_mask:0xf bank_mask:0xf
	s_not_b64 vcc, vcc
	v_cndmask_b32_dpp v42, v46, v42, vcc quad_perm:[1,0,3,2] row_mask:0xf bank_mask:0xf
;     __device__ __forceinline__ void operator()(const f32x4 (&acc)[2][2][4][2], const Unit& u, int wr, int wc, int fr, int fq) const {
;         const int rowb = u.pm * BM - row0 + wr * 64 + fr, col0 = u.pn * BM + wc * 32 + 4 * fq; float* Ob = O + (size_t)u.pk * pstride;
; #pragma unroll
;         for (int ai = 0; ai < 2; ++ai)
; #pragma unroll
;             for (int m = 0; m < 4; ++m) {
;                 const size_t off = (size_t)(rowb + ai * HALF + m * 16) * ldc + col0;
; #pragma unroll
;                 for (int bj = 0; bj < 2; ++bj)
; #pragma unroll
;                     for (int n = 0; n < 2; ++n) *(f32x4*)(Ob + off + bj * HALF + n * 16) = acc[ai][bj][m][n];
;             }
	v_cndmask_b32_dpp v43, v47, v43, vcc quad_perm:[1,0,3,2] row_mask:0xf bank_mask:0xf
	v_cndmask_b32_dpp v44, v48, v44, vcc quad_perm:[1,0,3,2] row_mask:0xf bank_mask:0xf
	v_cndmask_b32_dpp v45, v49, v45, vcc quad_perm:[1,0,3,2] row_mask:0xf bank_mask:0xf
	v_cndmask_b32_dpp v34, v38, v34, vcc quad_perm:[1,0,3,2] row_mask:0xf bank_mask:0xf
	v_cndmask_b32_dpp v35, v39, v35, vcc quad_perm:[1,0,3,2] row_mask:0xf bank_mask:0xf
	v_cndmask_b32_dpp v36, v40, v36, vcc quad_perm:[1,0,3,2] row_mask:0xf bank_mask:0xf
	v_cndmask_b32_dpp v37, v41, v37, vcc quad_perm:[1,0,3,2] row_mask:0xf bank_mask:0xf
	s_not_b64 vcc, vcc
	global_store_dwordx4 v[148:149], v[162:165], off offset:-4096
	global_store_dwordx4 v[148:149], v[166:169], off offset:-3584
	global_store_dwordx4 v[148:149], v[42:45], off
	global_store_dwordx4 v[148:149], v[34:37], off offset:512
	s_nop 1
	v_lshl_add_u64 v[148:149], v[148:149], 0, s[98:99]
	v_cndmask_b32_dpp v150, v26, v30, vcc quad_perm:[1,0,3,2] row_mask:0xf bank_mask:0xf
	v_cndmask_b32_dpp v151, v27, v31, vcc quad_perm:[1,0,3,2] row_mask:0xf bank_mask:0xf
	v_cndmask_b32_dpp v152, v28, v32, vcc quad_perm:[1,0,3,2] row_mask:0xf bank_mask:0xf
	v_cndmask_b32_dpp v153, v29, v33, vcc quad_perm:[1,0,3,2] row_mask:0xf bank_mask:0xf
	v_cndmask_b32_dpp v154, v18, v22, vcc quad_perm:[1,0,3,2] row_mask:0xf bank_mask:0xf
	v_cndmask_b32_dpp v155, v19, v23, vcc quad_perm:[1,0,3,2] row_mask:0xf bank_mask:0xf
	v_cndmask_b32_dpp v156, v20, v24, vcc quad_perm:[1,0,3,2] row_mask:0xf bank_mask:0xf
	v_cndmask_b32_dpp v157, v21, v25, vcc quad_perm:[1,0,3,2] row_mask:0xf bank_mask:0xf
	s_not_b64 vcc, vcc
	v_cndmask_b32_dpp v26, v30, v26, vcc quad_perm:[1,0,3,2] row_mask:0xf bank_mask:0xf
	v_cndmask_b32_dpp v27, v31, v27, vcc quad_perm:[1,0,3,2] row_mask:0xf bank_mask:0xf
	v_cndmask_b32_dpp v28, v32, v28, vcc quad_perm:[1,0,3,2] row_mask:0xf bank_mask:0xf
	v_cndmask_b32_dpp v29, v33, v29, vcc quad_perm:[1,0,3,2] row_mask:0xf bank_mask:0xf
	v_cndmask_b32_dpp v18, v22, v18, vcc quad_perm:[1,0,3,2] row_mask:0xf bank_mask:0xf
	v_cndmask_b32_dpp v19, v23, v19, vcc quad_perm:[1,0,3,2] row_mask:0xf bank_mask:0xf
	v_cndmask_b32_dpp v20, v24, v20, vcc quad_perm:[1,0,3,2] row_mask:0xf bank_mask:0xf
	v_cndmask_b32_dpp v21, v25, v21, vcc quad_perm:[1,0,3,2] row_mask:0xf bank_mask:0xf
	s_not_b64 vcc, vcc
	global_store_dwordx4 v[148:149], v[150:153], off offset:-4096
	global_store_dwordx4 v[148:149], v[154:157], off offset:-3584
	global_store_dwordx4 v[148:149], v[26:29], off
	global_store_dwordx4 v[148:149], v[18:21], off offset:512
	s_nop 1
	v_lshl_add_u64 v[148:149], v[148:149], 0, s[98:99]
	v_cndmask_b32_dpp v162, v10, v14, vcc quad_perm:[1,0,3,2] row_mask:0xf bank_mask:0xf
	v_cndmask_b32_dpp v163, v11, v15, vcc quad_perm:[1,0,3,2] row_mask:0xf bank_mask:0xf
	v_cndmask_b32_dpp v164, v12, v16, vcc quad_perm:[1,0,3,2] row_mask:0xf bank_mask:0xf
	v_cndmask_b32_dpp v165, v13, v17, vcc quad_perm:[1,0,3,2] row_mask:0xf bank_mask:0xf
	v_cndmask_b32_dpp v166, v2, v6, vcc quad_perm:[1,0,3,2] row_mask:0xf bank_mask:0xf
	v_cndmask_b32_dpp v167, v3, v7, vcc quad_perm:[1,0,3,2] row_mask:0xf bank_mask:0xf
	v_cndmask_b32_dpp v168, v4, v8, vcc quad_perm:[1,0,3,2] row_mask:0xf bank_mask:0xf
	v_cndmask_b32_dpp v169, v5, v9, vcc quad_perm:[1,0,3,2] row_mask:0xf bank_mask:0xf
	s_not_b64 vcc, vcc
	v_cndmask_b32_dpp v10, v14, v10, vcc quad_perm:[1,0,3,2] row_mask:0xf bank_mask:0xf
	v_cndmask_b32_dpp v11, v15, v11, vcc quad_perm:[1,0,3,2] row_mask:0xf bank_mask:0xf
	v_cndmask_b32_dpp v12, v16, v12, vcc quad_perm:[1,0,3,2] row_mask:0xf bank_mask:0xf
	v_cndmask_b32_dpp v13, v17, v13, vcc quad_perm:[1,0,3,2] row_mask:0xf bank_mask:0xf
	v_cndmask_b32_dpp v2, v6, v2, vcc quad_perm:[1,0,3,2] row_mask:0xf bank_mask:0xf
	v_cndmask_b32_dpp v3, v7, v3, vcc quad_perm:[1,0,3,2] row_mask:0xf bank_mask:0xf
	v_cndmask_b32_dpp v4, v8, v4, vcc quad_perm:[1,0,3,2] row_mask:0xf bank_mask:0xf
	v_cndmask_b32_dpp v5, v9, v5, vcc quad_perm:[1,0,3,2] row_mask:0xf bank_mask:0xf
	s_not_b64 vcc, vcc
	global_store_dwordx4 v[148:149], v[162:165], off offset:-4096
	global_store_dwordx4 v[148:149], v[166:169], off offset:-3584
	global_store_dwordx4 v[148:149], v[10:13], off
	global_store_dwordx4 v[148:149], v[2:5], off offset:512
	s_and_b64 vcc, exec, s[6:7]
	s_mov_b64 s[6:7], -1
	s_cbranch_vccnz .LBB0_1473
	s_andn2_b64 vcc, exec, s[14:15]
	s_cbranch_vccnz .LBB0_1472
	s_barrier
	s_branch .LBB0_1472

;     __device__ __forceinline__ void operator()(const f32x4 (&acc)[2][2][4][2], const Unit& u, int wr, int wc, int fr, int fq) const {
;         const int rowb = u.pm * BM - row0 + wr * 64 + fr, col0 = u.pn * BM + wc * 32 + 4 * fq; float* Ob = O + (size_t)u.pk * pstride;
; #pragma unroll
;         for (int ai = 0; ai < 2; ++ai)
; #pragma unroll
;             for (int m = 0; m < 4; ++m) {
;                 const size_t off = (size_t)(rowb + ai * HALF + m * 16) * ldc + col0;
; #pragma unroll
;                 for (int bj = 0; bj < 2; ++bj)
; #pragma unroll
;                     for (int n = 0; n < 2; ++n) *(f32x4*)(Ob + off + bj * HALF + n * 16) = acc[ai][bj][m][n];
;             }
.LBB0_1736:
	v_lshl_or_b32 v144, s25, 8, v139
	s_ashr_i32 s25, s24, 31
	s_lshl_b64 s[24:25], s[24:25], 22
	s_add_u32 s24, s10, s24
	v_lshl_add_u32 v146, s62, 8, v138
	s_addc_u32 s25, s11, s25
	v_ashrrev_i32_e32 v145, 31, v144
	v_ashrrev_i32_e32 v147, 31, v146
	v_lshl_add_u64 v[144:145], v[144:145], 2, s[24:25]
	v_lshlrev_b64 v[148:149], 12, v[146:147]
	v_lshl_add_u64 v[148:149], v[144:145], 0, v[148:149]
	v_and_b32_e32 v160, 1, v186
	v_cmp_eq_u32_e32 vcc, 0, v160
	v_xor_b32_e32 v160, 1, v160
	s_movk_i32 s98, 0xfc0
	v_mov_b32_e32 v159, 0
	v_mad_u32_u24 v158, v160, s98, 64
	s_mov_b32 s98, 0x10000
	s_mov_b32 s99, 0
	v_lshl_add_u64 v[148:149], v[148:149], 0, v[158:159]
	v_cndmask_b32_dpp v150, v122, v126, vcc quad_perm:[1,0,3,2] row_mask:0xf bank_mask:0xf
	v_cndmask_b32_dpp v151, v123, v127, vcc quad_perm:[1,0,3,2] row_mask:0xf bank_mask:0xf
	v_cndmask_b32_dpp v152, v124, v128, vcc quad_perm:[1,0,3,2] row_mask:0xf bank_mask:0xf
	v_cndmask_b32_dpp v153, v125, v129, vcc quad_perm:[1,0,3,2] row_mask:0xf bank_mask:0xf
	v_cndmask_b32_dpp v154, v114, v118, vcc quad_perm:[1,0,3,2] row_mask:0xf bank_mask:0xf
	v_cndmask_b32_dpp v155, v115, v119, vcc quad_perm:[1,0,3,2] row_mask:0xf bank_mask:0xf
	v_cndmask_b32_dpp v156, v116, v120, vcc quad_perm:[1,0,3,2] row_mask:0xf bank_mask:0xf
	v_cndmask_b32_dpp v157, v117, v121, vcc quad_perm:[1,0,3,2] row_mask:0xf bank_mask:0xf
	s_not_b64 vcc, vcc
	v_cndmask_b32_dpp v122, v126, v122, vcc quad_perm:[1,0,3,2] row_mask:0xf bank_mask:0xf
	v_cndmask_b32_dpp v123, v127, v123, vcc quad_perm:[1,0,3,2] row_mask:0xf bank_mask:0xf
	v_cndmask_b32_dpp v124, v128, v124, vcc quad_perm:[1,0,3,2] row_mask:0xf bank_mask:0xf
	v_cndmask_b32_dpp v125, v129, v125, vcc quad_perm:[1,0,3,2] row_mask:0xf bank_mask:0xf
	v_cndmask_b32_dpp v114, v118, v114, vcc quad_perm:[1,0,3,2] row_mask:0xf bank_mask:0xf
	v_cndmask_b32_dpp v115, v119, v115, vcc quad_perm:[1,0,3,2] row_mask:0xf bank_mask:0xf
	v_cndmask_b32_dpp v116, v120, v116, vcc quad_perm:[1,0,3,2] row_mask:0xf bank_mask:0xf
	v_cndmask_b32_dpp v117, v121, v117, vcc quad_perm:[1,0,3,2] row_mask:0xf bank_mask:0xf
	s_not_b64 vcc, vcc
	global_store_dwordx4 v[148:149], v[150:153], off offset:-4096
	global_store_dwordx4 v[148:149], v[154:157], off offset:-3584
	global_store_dwordx4 v[148:149], v[122:125], off
	global_store_dwordx4 v[148:149], v[114:117], off offset:512
	s_nop 1
	v_lshl_add_u64 v[148:149], v[148:149], 0, s[98:99]
	v_cndmask_b32_dpp v162, v106, v110, vcc quad_perm:[1,0,3,2] row_mask:0xf bank_mask:0xf
	v_cndmask_b32_dpp v163, v107, v111, vcc quad_perm:[1,0,3,2] row_mask:0xf bank_mask:0xf
	v_cndmask_b32_dpp v164, v108, v112, vcc quad_perm:[1,0,3,2] row_mask:0xf bank_mask:0xf
	v_cndmask_b32_dpp v165, v109, v113, vcc quad_perm:[1,0,3,2] row_mask:0xf bank_mask:0xf
	v_cndmask_b32_dpp v166, v98, v102, vcc quad_perm:[1,0,3,2] row_mask:0xf bank_mask:0xf
	v_cndmask_b32_dpp v167, v99, v103, vcc quad_perm:[1,0,3,2] row_mask:0xf bank_mask:0xf
	v_cndmask_b32_dpp v168, v100, v104, vcc quad_perm:[1,0,3,2] row_mask:0xf bank_mask:0xf
	v_cndmask_b32_dpp v169, v101, v105, vcc quad_perm:[1,0,3,2] row_mask:0xf bank_mask:0xf
	s_not_b64 vcc, vcc
	v_cndmask_b32_dpp v106, v110, v106, vcc quad_perm:[1,0,3,2] row_mask:0xf bank_mask:0xf
	v_cndmask_b32_dpp v107, v111, v107, vcc quad_perm:[1,0,3,2] row_mask:0xf bank_mask:0xf
	v_cndmask_b32_dpp v108, v112, v108, vcc quad_perm:[1,0,3,2] row_mask:0xf bank_mask:0xf
	v_cndmask_b32_dpp v109, v113, v109, vcc quad_perm:[1,0,3,2] row_mask:0xf bank_mask:0xf
	v_cndmask_b32_dpp v98, v102, v98, vcc quad_perm:[1,0,3,2] row_mask:0xf bank_mask:0xf
	v_cndmask_b32_dpp v99, v103, v99, vcc quad_perm:[1,0,3,2] row_mask:0xf bank_mask:0xf
	v_cndmask_b32_dpp v100, v104, v100, vcc quad_perm:[1,0,3,2] row_mask:0xf bank_mask:0xf
	v_cndmask_b32_dpp v101, v105, v101, vcc quad_perm:[1,0,3,2] row_mask:0xf bank_mask:0xf
	s_not_b64 vcc, vcc
	global_store_dwordx4 v[148:149], v[162:165], off offset:-4096
	global_store_dwordx4 v[148:149], v[166:169], off offset:-3584
	global_store_dwordx4 v[148:149], v[106:109], off
	global_store_dwordx4 v[148:149], v[98:101], off offset:512
	s_nop 1
	v_lshl_add_u64 v[148:149], v[148:149], 0, s[98:99]
	v_cndmask_b32_dpp v150, v90, v94, vcc quad_perm:[1,0,3,2] row_mask:0xf bank_mask:0xf
	v_cndmask_b32_dpp v151, v91, v95, vcc quad_perm:[1,0,3,2] row_mask:0xf bank_mask:0xf
	v_cndmask_b32_dpp v152, v92, v96, vcc quad_perm:[1,0,3,2] row_mask:0xf bank_mask:0xf
	v_cndmask_b32_dpp v153, v93, v97, vcc quad_perm:[1,0,3,2] row_mask:0xf bank_mask:0xf
	v_cndmask_b32_dpp v154, v82, v86, vcc quad_perm:[1,0,3,2] row_mask:0xf bank_mask:0xf
	v_cndmask_b32_dpp v155, v83, v87, vcc quad_perm:[1,0,3,2] row_mask:0xf bank_mask:0xf
	v_cndmask_b32_dpp v156, v84, v88, vcc quad_perm:[1,0,3,2] row_mask:0xf bank_mask:0xf
	v_cndmask_b32_dpp v157, v85, v89, vcc quad_perm:[1,0,3,2] row_mask:0xf bank_mask:0xf
	s_not_b64 vcc, vcc
	v_cndmask_b32_dpp v90, v94, v90, vcc quad_perm:[1,0,3,2] row_mask:0xf bank_mask:0xf
	v_cndmask_b32_dpp v91, v95, v91, vcc quad_perm:[1,0,3,2] row_mask:0xf bank_mask:0xf
	v_cndmask_b32_dpp v92, v96, v92, vcc quad_perm:[1,0,3,2] row_mask:0xf bank_mask:0xf
	v_cndmask_b32_dpp v93, v97, v93, vcc quad_perm:[1,0,3,2] row_mask:0xf bank_mask:0xf
	v_cndmask_b32_dpp v82, v86, v82, vcc quad_perm:[1,0,3,2] row_mask:0xf bank_mask:0xf
	v_cndmask_b32_dpp v83, v87, v83, vcc quad_perm:[1,0,3,2] row_mask:0xf bank_mask:0xf
	v_cndmask_b32_dpp v84, v88, v84, vcc quad_perm:[1,0,3,2] row_mask:0xf bank_mask:0xf
	v_cndmask_b32_dpp v85, v89, v85, vcc quad_perm:[1,0,3,2] row_mask:0xf bank_mask:0xf
	s_not_b64 vcc, vcc
	global_store_dwordx4 v[148:149], v[150:153], off offset:-4096
;     __device__ __forceinline__ void operator()(const f32x4 (&acc)[2][2][4][2], const Unit& u, int wr, int wc, int fr, int fq) const {
;         const int rowb = u.pm * BM - row0 + wr * 64 + fr, col0 = u.pn * BM + wc * 32 + 4 * fq; float* Ob = O + (size_t)u.pk * pstride;
; #pragma unroll
;         for (int ai = 0; ai < 2; ++ai)
; #pragma unroll
;             for (int m = 0; m < 4; ++m) {
;                 const size_t off = (size_t)(rowb + ai * HALF + m * 16) * ldc + col0;
; #pragma unroll
;                 for (int bj = 0; bj < 2; ++bj)
; #pragma unroll
;                     for (int n = 0; n < 2; ++n) *(f32x4*)(Ob + off + bj * HALF + n * 16) = acc[ai][bj][m][n];
;             }
	global_store_dwordx4 v[148:149], v[154:157], off offset:-3584
	global_store_dwordx4 v[148:149], v[90:93], off
	global_store_dwordx4 v[148:149], v[82:85], off offset:512
	s_nop 1
	v_lshl_add_u64 v[148:149], v[148:149], 0, s[98:99]
	v_cndmask_b32_dpp v162, v74, v78, vcc quad_perm:[1,0,3,2] row_mask:0xf bank_mask:0xf
	v_cndmask_b32_dpp v163, v75, v79, vcc quad_perm:[1,0,3,2] row_mask:0xf bank_mask:0xf
	v_cndmask_b32_dpp v164, v76, v80, vcc quad_perm:[1,0,3,2] row_mask:0xf bank_mask:0xf
	v_cndmask_b32_dpp v165, v77, v81, vcc quad_perm:[1,0,3,2] row_mask:0xf bank_mask:0xf
	v_cndmask_b32_dpp v166, v66, v70, vcc quad_perm:[1,0,3,2] row_mask:0xf bank_mask:0xf
	v_cndmask_b32_dpp v167, v67, v71, vcc quad_perm:[1,0,3,2] row_mask:0xf bank_mask:0xf
	v_cndmask_b32_dpp v168, v68, v72, vcc quad_perm:[1,0,3,2] row_mask:0xf bank_mask:0xf
	v_cndmask_b32_dpp v169, v69, v73, vcc quad_perm:[1,0,3,2] row_mask:0xf bank_mask:0xf
	s_not_b64 vcc, vcc
	v_cndmask_b32_dpp v74, v78, v74, vcc quad_perm:[1,0,3,2] row_mask:0xf bank_mask:0xf
	v_cndmask_b32_dpp v75, v79, v75, vcc quad_perm:[1,0,3,2] row_mask:0xf bank_mask:0xf
	v_cndmask_b32_dpp v76, v80, v76, vcc quad_perm:[1,0,3,2] row_mask:0xf bank_mask:0xf
	v_cndmask_b32_dpp v77, v81, v77, vcc quad_perm:[1,0,3,2] row_mask:0xf bank_mask:0xf
	v_cndmask_b32_dpp v66, v70, v66, vcc quad_perm:[1,0,3,2] row_mask:0xf bank_mask:0xf
	v_cndmask_b32_dpp v67, v71, v67, vcc quad_perm:[1,0,3,2] row_mask:0xf bank_mask:0xf
	v_cndmask_b32_dpp v68, v72, v68, vcc quad_perm:[1,0,3,2] row_mask:0xf bank_mask:0xf
	v_cndmask_b32_dpp v69, v73, v69, vcc quad_perm:[1,0,3,2] row_mask:0xf bank_mask:0xf
	s_not_b64 vcc, vcc
	global_store_dwordx4 v[148:149], v[162:165], off offset:-4096
	global_store_dwordx4 v[148:149], v[166:169], off offset:-3584
	global_store_dwordx4 v[148:149], v[74:77], off
	global_store_dwordx4 v[148:149], v[66:69], off offset:512
	s_mov_b32 s98, 0x50000
	s_nop 0
	v_lshl_add_u64 v[148:149], v[148:149], 0, s[98:99]
	s_mov_b32 s98, 0x10000
	v_cndmask_b32_dpp v150, v58, v62, vcc quad_perm:[1,0,3,2] row_mask:0xf bank_mask:0xf
	v_cndmask_b32_dpp v151, v59, v63, vcc quad_perm:[1,0,3,2] row_mask:0xf bank_mask:0xf
	v_cndmask_b32_dpp v152, v60, v64, vcc quad_perm:[1,0,3,2] row_mask:0xf bank_mask:0xf
	v_cndmask_b32_dpp v153, v61, v65, vcc quad_perm:[1,0,3,2] row_mask:0xf bank_mask:0xf
	v_cndmask_b32_dpp v154, v50, v54, vcc quad_perm:[1,0,3,2] row_mask:0xf bank_mask:0xf
	v_cndmask_b32_dpp v155, v51, v55, vcc quad_perm:[1,0,3,2] row_mask:0xf bank_mask:0xf
	v_cndmask_b32_dpp v156, v52, v56, vcc quad_perm:[1,0,3,2] row_mask:0xf bank_mask:0xf
	v_cndmask_b32_dpp v157, v53, v57, vcc quad_perm:[1,0,3,2] row_mask:0xf bank_mask:0xf
	s_not_b64 vcc, vcc
	v_cndmask_b32_dpp v58, v62, v58, vcc quad_perm:[1,0,3,2] row_mask:0xf bank_mask:0xf
	v_cndmask_b32_dpp v59, v63, v59, vcc quad_perm:[1,0,3,2] row_mask:0xf bank_mask:0xf
	v_cndmask_b32_dpp v60, v64, v60, vcc quad_perm:[1,0,3,2] row_mask:0xf bank_mask:0xf
	v_cndmask_b32_dpp v61, v65, v61, vcc quad_perm:[1,0,3,2] row_mask:0xf bank_mask:0xf
	v_cndmask_b32_dpp v50, v54, v50, vcc quad_perm:[1,0,3,2] row_mask:0xf bank_mask:0xf
	v_cndmask_b32_dpp v51, v55, v51, vcc quad_perm:[1,0,3,2] row_mask:0xf bank_mask:0xf
	v_cndmask_b32_dpp v52, v56, v52, vcc quad_perm:[1,0,3,2] row_mask:0xf bank_mask:0xf
	v_cndmask_b32_dpp v53, v57, v53, vcc quad_perm:[1,0,3,2] row_mask:0xf bank_mask:0xf
	s_not_b64 vcc, vcc
	global_store_dwordx4 v[148:149], v[150:153], off offset:-4096
	global_store_dwordx4 v[148:149], v[154:157], off offset:-3584
	global_store_dwordx4 v[148:149], v[58:61], off
	global_store_dwordx4 v[148:149], v[50:53], off offset:512
	s_nop 1
	v_lshl_add_u64 v[148:149], v[148:149], 0, s[98:99]
	v_cndmask_b32_dpp v162, v42, v46, vcc quad_perm:[1,0,3,2] row_mask:0xf bank_mask:0xf
	v_cndmask_b32_dpp v163, v43, v47, vcc quad_perm:[1,0,3,2] row_mask:0xf bank_mask:0xf
	v_cndmask_b32_dpp v164, v44, v48, vcc quad_perm:[1,0,3,2] row_mask:0xf bank_mask:0xf
	v_cndmask_b32_dpp v165, v45, v49, vcc quad_perm:[1,0,3,2] row_mask:0xf bank_mask:0xf
	v_cndmask_b32_dpp v166, v34, v38, vcc quad_perm:[1,0,3,2] row_mask:0xf bank_mask:0xf
	v_cndmask_b32_dpp v167, v35, v39, vcc quad_perm:[1,0,3,2] row_mask:0xf bank_mask:0xf
	v_cndmask_b32_dpp v168, v36, v40, vcc quad_perm:[1,0,3,2] row_mask:0xf bank_mask:0xf
	v_cndmask_b32_dpp v169, v37, v41, vcc quad_perm:[1,0,3,2] row_mask:0xf bank_mask:0xf
	s_not_b64 vcc, vcc
	v_cndmask_b32_dpp v42, v46, v42, vcc quad_perm:[1,0,3,2] row_mask:0xf bank_mask:0xf
;     __device__ __forceinline__ void operator()(const f32x4 (&acc)[2][2][4][2], const Unit& u, int wr, int wc, int fr, int fq) const {
;         const int rowb = u.pm * BM - row0 + wr * 64 + fr, col0 = u.pn * BM + wc * 32 + 4 * fq; float* Ob = O + (size_t)u.pk * pstride;
; #pragma unroll
;         for (int ai = 0; ai < 2; ++ai)
; #pragma unroll
;             for (int m = 0; m < 4; ++m) {
;                 const size_t off = (size_t)(rowb + ai * HALF + m * 16) * ldc + col0;
; #pragma unroll
;                 for (int bj = 0; bj < 2; ++bj)
; #pragma unroll
;                     for (int n = 0; n < 2; ++n) *(f32x4*)(Ob + off + bj * HALF + n * 16) = acc[ai][bj][m][n];
;             }
	v_cndmask_b32_dpp v43, v47, v43, vcc quad_perm:[1,0,3,2] row_mask:0xf bank_mask:0xf
	v_cndmask_b32_dpp v44, v48, v44, vcc quad_perm:[1,0,3,2] row_mask:0xf bank_mask:0xf
	v_cndmask_b32_dpp v45, v49, v45, vcc quad_perm:[1,0,3,2] row_mask:0xf bank_mask:0xf
	v_cndmask_b32_dpp v34, v38, v34, vcc quad_perm:[1,0,3,2] row_mask:0xf bank_mask:0xf
	v_cndmask_b32_dpp v35, v39, v35, vcc quad_perm:[1,0,3,2] row_mask:0xf bank_mask:0xf
	v_cndmask_b32_dpp v36, v40, v36, vcc quad_perm:[1,0,3,2] row_mask:0xf bank_mask:0xf
	v_cndmask_b32_dpp v37, v41, v37, vcc quad_perm:[1,0,3,2] row_mask:0xf bank_mask:0xf
	s_not_b64 vcc, vcc
	global_store_dwordx4 v[148:149], v[162:165], off offset:-4096
	global_store_dwordx4 v[148:149], v[166:169], off offset:-3584
	global_store_dwordx4 v[148:149], v[42:45], off
	global_store_dwordx4 v[148:149], v[34:37], off offset:512
	s_nop 1
	v_lshl_add_u64 v[148:149], v[148:149], 0, s[98:99]
	v_cndmask_b32_dpp v150, v26, v30, vcc quad_perm:[1,0,3,2] row_mask:0xf bank_mask:0xf
	v_cndmask_b32_dpp v151, v27, v31, vcc quad_perm:[1,0,3,2] row_mask:0xf bank_mask:0xf
	v_cndmask_b32_dpp v152, v28, v32, vcc quad_perm:[1,0,3,2] row_mask:0xf bank_mask:0xf
	v_cndmask_b32_dpp v153, v29, v33, vcc quad_perm:[1,0,3,2] row_mask:0xf bank_mask:0xf
	v_cndmask_b32_dpp v154, v18, v22, vcc quad_perm:[1,0,3,2] row_mask:0xf bank_mask:0xf
	v_cndmask_b32_dpp v155, v19, v23, vcc quad_perm:[1,0,3,2] row_mask:0xf bank_mask:0xf
	v_cndmask_b32_dpp v156, v20, v24, vcc quad_perm:[1,0,3,2] row_mask:0xf bank_mask:0xf
	v_cndmask_b32_dpp v157, v21, v25, vcc quad_perm:[1,0,3,2] row_mask:0xf bank_mask:0xf
	s_not_b64 vcc, vcc
	v_cndmask_b32_dpp v26, v30, v26, vcc quad_perm:[1,0,3,2] row_mask:0xf bank_mask:0xf
	v_cndmask_b32_dpp v27, v31, v27, vcc quad_perm:[1,0,3,2] row_mask:0xf bank_mask:0xf
	v_cndmask_b32_dpp v28, v32, v28, vcc quad_perm:[1,0,3,2] row_mask:0xf bank_mask:0xf
	v_cndmask_b32_dpp v29, v33, v29, vcc quad_perm:[1,0,3,2] row_mask:0xf bank_mask:0xf
	v_cndmask_b32_dpp v18, v22, v18, vcc quad_perm:[1,0,3,2] row_mask:0xf bank_mask:0xf
	v_cndmask_b32_dpp v19, v23, v19, vcc quad_perm:[1,0,3,2] row_mask:0xf bank_mask:0xf
	v_cndmask_b32_dpp v20, v24, v20, vcc quad_perm:[1,0,3,2] row_mask:0xf bank_mask:0xf
	v_cndmask_b32_dpp v21, v25, v21, vcc quad_perm:[1,0,3,2] row_mask:0xf bank_mask:0xf
	s_not_b64 vcc, vcc
	global_store_dwordx4 v[148:149], v[150:153], off offset:-4096
	global_store_dwordx4 v[148:149], v[154:157], off offset:-3584
	global_store_dwordx4 v[148:149], v[26:29], off
	global_store_dwordx4 v[148:149], v[18:21], off offset:512
	s_nop 1
	v_lshl_add_u64 v[148:149], v[148:149], 0, s[98:99]
	v_cndmask_b32_dpp v162, v10, v14, vcc quad_perm:[1,0,3,2] row_mask:0xf bank_mask:0xf
	v_cndmask_b32_dpp v163, v11, v15, vcc quad_perm:[1,0,3,2] row_mask:0xf bank_mask:0xf
	v_cndmask_b32_dpp v164, v12, v16, vcc quad_perm:[1,0,3,2] row_mask:0xf bank_mask:0xf
	v_cndmask_b32_dpp v165, v13, v17, vcc quad_perm:[1,0,3,2] row_mask:0xf bank_mask:0xf
	v_cndmask_b32_dpp v166, v2, v6, vcc quad_perm:[1,0,3,2] row_mask:0xf bank_mask:0xf
	v_cndmask_b32_dpp v167, v3, v7, vcc quad_perm:[1,0,3,2] row_mask:0xf bank_mask:0xf
	v_cndmask_b32_dpp v168, v4, v8, vcc quad_perm:[1,0,3,2] row_mask:0xf bank_mask:0xf
	v_cndmask_b32_dpp v169, v5, v9, vcc quad_perm:[1,0,3,2] row_mask:0xf bank_mask:0xf
	s_not_b64 vcc, vcc
	v_cndmask_b32_dpp v10, v14, v10, vcc quad_perm:[1,0,3,2] row_mask:0xf bank_mask:0xf
	v_cndmask_b32_dpp v11, v15, v11, vcc quad_perm:[1,0,3,2] row_mask:0xf bank_mask:0xf
	v_cndmask_b32_dpp v12, v16, v12, vcc quad_perm:[1,0,3,2] row_mask:0xf bank_mask:0xf
	v_cndmask_b32_dpp v13, v17, v13, vcc quad_perm:[1,0,3,2] row_mask:0xf bank_mask:0xf
	v_cndmask_b32_dpp v2, v6, v2, vcc quad_perm:[1,0,3,2] row_mask:0xf bank_mask:0xf
	v_cndmask_b32_dpp v3, v7, v3, vcc quad_perm:[1,0,3,2] row_mask:0xf bank_mask:0xf
	v_cndmask_b32_dpp v4, v8, v4, vcc quad_perm:[1,0,3,2] row_mask:0xf bank_mask:0xf
	v_cndmask_b32_dpp v5, v9, v5, vcc quad_perm:[1,0,3,2] row_mask:0xf bank_mask:0xf
	s_not_b64 vcc, vcc
	global_store_dwordx4 v[148:149], v[162:165], off offset:-4096
	global_store_dwordx4 v[148:149], v[166:169], off offset:-3584
	global_store_dwordx4 v[148:149], v[10:13], off
	global_store_dwordx4 v[148:149], v[2:5], off offset:512
	s_and_b64 vcc, exec, s[4:5]
	s_mov_b64 s[4:5], -1
	s_cbranch_vccnz .LBB0_1724
	s_andn2_b64 vcc, exec, s[12:13]
	s_cbranch_vccnz .LBB0_1723
	s_barrier
	s_branch .LBB0_1723
